# redundant end-of-phase vmcnt(0)+s_barrier removed where the next seam barrier follows directly (5 sites): setup code overlaps the store drain
# speedup vs baseline: 1.0106x; 1.0106x over previous
.LBB0_943:
.LBB0_944:
	s_branch .LBB0_991

.LBB0_1591:
	s_or_b64 exec, exec, s[4:5]
.LBB0_1592:
	s_mov_b64 s[4:5], s[20:21]
	s_mov_b32 s2, 0x22174
	s_add_i32 s2, s2, 0
	v_mov_b32_e32 v0, s2
	ds_read_b32 v0, v0
	s_load_dwordx2 s[2:3], s[0:1], 0xd0
	v_readlane_b32 s6, v255, 20
	s_waitcnt lgkmcnt(0)
	v_readlane_b32 s7, v255, 21
	s_add_u32 s37, s2, s6
	v_readfirstlane_b32 s65, v0
	s_addc_u32 s64, s3, s7
	s_cmpk_lt_u32 s65, 0x100
	s_cselect_b64 s[6:7], -1, 0
	s_cmpk_gt_u32 s65, 0xff
	s_cbranch_scc1 .LBB0_1594
	s_lshl_b32 s2, s65, 23
	s_lshl_b32 s3, s65, 13
	s_and_b32 s2, s2, 0x3800000
	s_and_b32 s3, s3, 0x180000
	s_add_u32 s3, s37, s3
	s_addc_u32 s8, s64, 0
	s_add_u32 s2, s3, s2
	s_addc_u32 s3, s8, 0
	v_writelane_b32 v255, s2, 36
	s_nop 1
	v_writelane_b32 v255, s3, 37

.LBB0_1684:
	s_mov_b64 s[2:3], 0x6300000
	v_add_u32_e32 v130, s41, v133
	v_lshl_add_u32 v132, s14, 8, v130
	v_ashrrev_i32_e32 v133, 31, v132
	v_lshlrev_b64 v[132:133], 6, v[132:133]
	v_lshl_add_u64 v[142:143], s[4:5], 0, v[132:133]
	v_lshl_add_u64 v[132:133], v[142:143], 0, s[2:3]
	v_add_co_u32_e32 v142, vcc, 0x6300000, v142
	global_load_dwordx4 v[134:137], v[132:133], off offset:16 sc1
	global_load_dwordx4 v[138:141], v[132:133], off offset:32 sc1
	v_addc_co_u32_e32 v143, vcc, 0, v143, vcc
	global_load_dwordx4 v[142:145], v[142:143], off sc1
	s_nop 0
	global_load_dwordx4 v[146:149], v[132:133], off offset:48 sc1
	s_mov_b32 s2, 0xff61b1e6
	s_waitcnt vmcnt(0)
	v_mov_b32_e32 v154, v134
	v_mov_b32_e32 v151, v138
	v_mov_b32_e32 v153, v140
	v_mov_b32_e32 v134, v136
	v_mov_b32_e32 v150, v142
	v_mov_b32_e32 v138, v143
	v_mov_b32_e32 v152, v144
	v_mov_b32_e32 v140, v145
	v_mov_b32_e32 v155, v146
	v_mov_b32_e32 v146, v135
	v_mov_b32_e32 v135, v148
	v_mov_b32_e32 v148, v137
	v_pk_add_f32 v[136:137], v[150:151], v[138:139]
	v_pk_add_f32 v[138:139], v[152:153], v[140:141]
	v_pk_add_f32 v[140:141], v[154:155], v[146:147]
	v_pk_add_f32 v[134:135], v[134:135], v[148:149]
	v_pk_add_f32 v[136:137], v[136:137], v[138:139]
	v_pk_add_f32 v[134:135], v[140:141], v[134:135]
	s_nop 0
	v_pk_add_f32 v[134:135], v[136:137], v[134:135]
	s_nop 0
	v_add_f32_e32 v0, v134, v135
	v_fmamk_f32 v0, v0, 0x3a800000, v231
	v_rsq_f32_e32 v0, v0
	s_nop 0
	v_pk_mul_f32 v[128:129], v[128:129], v[0:1] op_sel_hi:[1,0]
	v_pk_mul_f32 v[124:125], v[124:125], v[0:1] op_sel_hi:[1,0]
	v_pk_mul_f32 v[126:127], v[126:127], v[0:1] op_sel_hi:[1,0]
	v_pk_mul_f32 v[122:123], v[122:123], v[0:1] op_sel_hi:[1,0]
	v_pk_mul_f32 v[120:121], v[120:121], v[0:1] op_sel_hi:[1,0]
	v_pk_mul_f32 v[118:119], v[118:119], v[0:1] op_sel_hi:[1,0]
	v_pk_mul_f32 v[116:117], v[116:117], v[0:1] op_sel_hi:[1,0]
	v_pk_mul_f32 v[114:115], v[114:115], v[0:1] op_sel_hi:[1,0]
	v_max_f32_e32 v0, v128, v129
	v_max_f32_e32 v134, v124, v125
	v_max_f32_e32 v135, v120, v121
	v_max_f32_e32 v136, v116, v117
	v_max3_f32 v0, v126, v127, v0
	v_max3_f32 v134, v122, v123, v134
	v_max3_f32 v135, v118, v119, v135
	v_max3_f32 v136, v114, v115, v136
	v_max3_f32 v0, v0, s2, v134
	v_max3_f32 v0, v0, v135, v136
	ds_swizzle_b32 v134, v0 offset:swizzle(SWAP,16)
	s_lshl_b32 s2, s16, 2
	s_add_i32 s8, s2, 0
	v_cmp_eq_u32_e64 s[2:3], 0, v131
	s_add_i32 s9, s8, 0x20000
	s_waitcnt lgkmcnt(0)
	v_max_f32_e32 v134, v134, v134
	v_max_f32_e32 v0, v0, v134
	v_mov_b32_e32 v134, v0
	s_nop 1
	v_permlane32_swap_b32_e32 v0, v134
	s_and_saveexec_b64 s[6:7], s[2:3]
	v_max_f32_e32 v0, v0, v0
	v_max_f32_e32 v134, v134, v134
	v_lshl_add_u32 v135, v130, 4, s9
	v_max_f32_e32 v0, v0, v134
	ds_write_b32 v135, v0
	s_or_b64 exec, exec, s[6:7]
	global_load_dwordx4 v[134:137], v[132:133], off offset:1024 sc1
	global_load_dwordx4 v[138:141], v[132:133], off offset:1056 sc1
	global_load_dwordx4 v[142:145], v[132:133], off offset:1040 sc1
	global_load_dwordx4 v[146:149], v[132:133], off offset:1072 sc1
	s_mov_b32 s6, 0xff61b1e6
	s_waitcnt vmcnt(3)
	v_mov_b32_e32 v150, v134
	s_waitcnt vmcnt(2)
	v_mov_b32_e32 v151, v138
	v_mov_b32_e32 v138, v135
	v_mov_b32_e32 v134, v136
	v_mov_b32_e32 v135, v140
	v_mov_b32_e32 v140, v137
	s_waitcnt vmcnt(1)
	v_mov_b32_e32 v136, v142
	s_waitcnt vmcnt(0)
	v_mov_b32_e32 v137, v146
	v_mov_b32_e32 v146, v143
	v_mov_b32_e32 v142, v144
	v_mov_b32_e32 v143, v148
	v_mov_b32_e32 v148, v145
	v_pk_add_f32 v[138:139], v[150:151], v[138:139]
	v_pk_add_f32 v[134:135], v[134:135], v[140:141]
	v_pk_add_f32 v[136:137], v[136:137], v[146:147]
	v_pk_add_f32 v[140:141], v[142:143], v[148:149]
	v_pk_add_f32 v[134:135], v[138:139], v[134:135]
	v_pk_add_f32 v[136:137], v[136:137], v[140:141]
	v_add_u32_e32 v140, 16, v130
	v_pk_add_f32 v[134:135], v[134:135], v[136:137]
	s_nop 0
	v_add_f32_e32 v0, v134, v135
	v_fmamk_f32 v0, v0, 0x3a800000, v231
	v_rsq_f32_e32 v0, v0
	s_nop 0
	v_pk_mul_f32 v[112:113], v[112:113], v[0:1] op_sel_hi:[1,0]
	v_pk_mul_f32 v[108:109], v[108:109], v[0:1] op_sel_hi:[1,0]
	v_pk_mul_f32 v[110:111], v[110:111], v[0:1] op_sel_hi:[1,0]
	v_pk_mul_f32 v[106:107], v[106:107], v[0:1] op_sel_hi:[1,0]
	v_pk_mul_f32 v[104:105], v[104:105], v[0:1] op_sel_hi:[1,0]
	v_pk_mul_f32 v[102:103], v[102:103], v[0:1] op_sel_hi:[1,0]
	v_pk_mul_f32 v[100:101], v[100:101], v[0:1] op_sel_hi:[1,0]
	v_pk_mul_f32 v[98:99], v[98:99], v[0:1] op_sel_hi:[1,0]
	v_max_f32_e32 v0, v112, v113
	v_max_f32_e32 v134, v108, v109
	v_max_f32_e32 v135, v104, v105
	v_max_f32_e32 v136, v100, v101
	v_max3_f32 v0, v110, v111, v0
	v_max3_f32 v134, v106, v107, v134
	v_max3_f32 v135, v102, v103, v135
	v_max3_f32 v136, v98, v99, v136
	v_max3_f32 v0, v0, s6, v134
	v_max3_f32 v0, v0, v135, v136
	ds_swizzle_b32 v134, v0 offset:swizzle(SWAP,16)
	s_waitcnt lgkmcnt(0)
	v_max_f32_e32 v134, v134, v134
	v_max_f32_e32 v0, v0, v134
	v_mov_b32_e32 v134, v0
	s_nop 1
	v_permlane32_swap_b32_e32 v0, v134
	s_and_saveexec_b64 s[6:7], s[2:3]
	v_max_f32_e32 v0, v0, v0
	v_max_f32_e32 v134, v134, v134
	v_lshl_add_u32 v135, v140, 4, s9
	v_max_f32_e32 v0, v0, v134
	ds_write_b32 v135, v0
	s_or_b64 exec, exec, s[6:7]
	global_load_dwordx4 v[134:137], v[132:133], off offset:2048 sc1
	global_load_dwordx4 v[142:145], v[132:133], off offset:2080 sc1
	global_load_dwordx4 v[146:149], v[132:133], off offset:2064 sc1
	global_load_dwordx4 v[150:153], v[132:133], off offset:2096 sc1
	s_mov_b32 s6, 0xff61b1e6
	v_add_u32_e32 v141, 32, v130
	s_waitcnt vmcnt(3)
	v_mov_b32_e32 v138, v134
	s_waitcnt vmcnt(2)
	v_mov_b32_e32 v139, v142
	v_mov_b32_e32 v142, v135
	v_mov_b32_e32 v134, v136
	v_mov_b32_e32 v135, v144
	v_mov_b32_e32 v144, v137
	s_waitcnt vmcnt(1)
	v_mov_b32_e32 v136, v146
	s_waitcnt vmcnt(0)
	v_mov_b32_e32 v137, v150
	v_mov_b32_e32 v150, v147
	v_mov_b32_e32 v146, v148
	v_mov_b32_e32 v147, v152
	v_mov_b32_e32 v152, v149
	v_pk_add_f32 v[138:139], v[138:139], v[142:143]
	v_pk_add_f32 v[134:135], v[134:135], v[144:145]
	v_pk_add_f32 v[136:137], v[136:137], v[150:151]
	v_pk_add_f32 v[142:143], v[146:147], v[152:153]
	v_pk_add_f32 v[134:135], v[138:139], v[134:135]
	v_pk_add_f32 v[136:137], v[136:137], v[142:143]
	s_nop 0
	v_pk_add_f32 v[134:135], v[134:135], v[136:137]
	s_nop 0
	v_add_f32_e32 v0, v134, v135
	v_fmamk_f32 v0, v0, 0x3a800000, v231
	v_rsq_f32_e32 v0, v0
	s_nop 0
	v_pk_mul_f32 v[96:97], v[96:97], v[0:1] op_sel_hi:[1,0]
	v_pk_mul_f32 v[92:93], v[92:93], v[0:1] op_sel_hi:[1,0]
	v_pk_mul_f32 v[94:95], v[94:95], v[0:1] op_sel_hi:[1,0]
	v_pk_mul_f32 v[90:91], v[90:91], v[0:1] op_sel_hi:[1,0]
	v_pk_mul_f32 v[88:89], v[88:89], v[0:1] op_sel_hi:[1,0]
	v_pk_mul_f32 v[86:87], v[86:87], v[0:1] op_sel_hi:[1,0]
	v_pk_mul_f32 v[84:85], v[84:85], v[0:1] op_sel_hi:[1,0]
	v_pk_mul_f32 v[82:83], v[82:83], v[0:1] op_sel_hi:[1,0]
	v_max_f32_e32 v0, v96, v97
	v_max_f32_e32 v134, v92, v93
	v_max_f32_e32 v135, v88, v89
	v_max_f32_e32 v136, v84, v85
	v_max3_f32 v0, v94, v95, v0
	v_max3_f32 v134, v90, v91, v134
	v_max3_f32 v135, v86, v87, v135
	v_max3_f32 v136, v82, v83, v136
	v_max3_f32 v0, v0, s6, v134
	v_max3_f32 v0, v0, v135, v136
	ds_swizzle_b32 v134, v0 offset:swizzle(SWAP,16)
	s_waitcnt lgkmcnt(0)
	v_max_f32_e32 v134, v134, v134
	v_max_f32_e32 v0, v0, v134
	v_mov_b32_e32 v134, v0
	s_nop 1
	v_permlane32_swap_b32_e32 v0, v134
	s_and_saveexec_b64 s[6:7], s[2:3]
	v_max_f32_e32 v0, v0, v0
	v_max_f32_e32 v134, v134, v134
	v_lshl_add_u32 v135, v141, 4, s9
	v_max_f32_e32 v0, v0, v134
	ds_write_b32 v135, v0
	s_or_b64 exec, exec, s[6:7]
	global_load_dwordx4 v[134:137], v[132:133], off offset:3072 sc1
	global_load_dwordx4 v[142:145], v[132:133], off offset:3104 sc1
	global_load_dwordx4 v[146:149], v[132:133], off offset:3088 sc1
	global_load_dwordx4 v[150:153], v[132:133], off offset:3120 sc1
	s_mov_b32 s6, 0xff61b1e6
	s_waitcnt vmcnt(3)
	v_mov_b32_e32 v138, v134
	s_waitcnt vmcnt(2)
	v_mov_b32_e32 v139, v142
	v_mov_b32_e32 v142, v135
	v_mov_b32_e32 v134, v136
	v_mov_b32_e32 v135, v144
	v_mov_b32_e32 v144, v137
	s_waitcnt vmcnt(1)
	v_mov_b32_e32 v136, v146
	s_waitcnt vmcnt(0)
	v_mov_b32_e32 v137, v150
	v_mov_b32_e32 v150, v147
	v_mov_b32_e32 v146, v148
	v_mov_b32_e32 v147, v152
	v_mov_b32_e32 v152, v149
	v_pk_add_f32 v[138:139], v[138:139], v[142:143]
	v_pk_add_f32 v[134:135], v[134:135], v[144:145]
	v_pk_add_f32 v[136:137], v[136:137], v[150:151]
	v_pk_add_f32 v[142:143], v[146:147], v[152:153]
	v_pk_add_f32 v[134:135], v[138:139], v[134:135]
	v_pk_add_f32 v[136:137], v[136:137], v[142:143]
	v_add_u32_e32 v142, 48, v130
	v_pk_add_f32 v[134:135], v[134:135], v[136:137]
	s_nop 0
	v_add_f32_e32 v0, v134, v135
	v_fmamk_f32 v0, v0, 0x3a800000, v231
	v_rsq_f32_e32 v0, v0
	s_nop 0
	v_pk_mul_f32 v[80:81], v[80:81], v[0:1] op_sel_hi:[1,0]
	v_pk_mul_f32 v[76:77], v[76:77], v[0:1] op_sel_hi:[1,0]
	v_pk_mul_f32 v[78:79], v[78:79], v[0:1] op_sel_hi:[1,0]
	v_pk_mul_f32 v[74:75], v[74:75], v[0:1] op_sel_hi:[1,0]
	v_pk_mul_f32 v[72:73], v[72:73], v[0:1] op_sel_hi:[1,0]
	v_pk_mul_f32 v[70:71], v[70:71], v[0:1] op_sel_hi:[1,0]
	v_pk_mul_f32 v[68:69], v[68:69], v[0:1] op_sel_hi:[1,0]
	v_pk_mul_f32 v[66:67], v[66:67], v[0:1] op_sel_hi:[1,0]
	v_max_f32_e32 v0, v80, v81
	v_max_f32_e32 v134, v76, v77
	v_max_f32_e32 v135, v72, v73
	v_max_f32_e32 v136, v68, v69
	v_max3_f32 v0, v78, v79, v0
	v_max3_f32 v134, v74, v75, v134
	v_max3_f32 v135, v70, v71, v135
	v_max3_f32 v136, v66, v67, v136
	v_max3_f32 v0, v0, s6, v134
	v_max3_f32 v0, v0, v135, v136
	ds_swizzle_b32 v134, v0 offset:swizzle(SWAP,16)
	s_waitcnt lgkmcnt(0)
	v_max_f32_e32 v134, v134, v134
	v_max_f32_e32 v0, v0, v134
	v_mov_b32_e32 v134, v0
	s_nop 1
	v_permlane32_swap_b32_e32 v0, v134
	s_and_saveexec_b64 s[6:7], s[2:3]
	v_max_f32_e32 v0, v0, v0
	v_max_f32_e32 v134, v134, v134
	v_lshl_add_u32 v135, v142, 4, s9
	v_max_f32_e32 v0, v0, v134
	ds_write_b32 v135, v0
	s_or_b64 exec, exec, s[6:7]
	v_add_co_u32_e32 v134, vcc, 0x2000, v132
	s_mov_b64 s[6:7], 0x2000
	s_nop 0
	v_addc_co_u32_e32 v135, vcc, 0, v133, vcc
	v_lshl_add_u64 v[138:139], v[132:133], 0, s[6:7]
	global_load_dwordx4 v[134:137], v[134:135], off sc1
	s_nop 0
	global_load_dwordx4 v[144:147], v[138:139], off offset:16 sc1
	global_load_dwordx4 v[148:151], v[138:139], off offset:48 sc1
	global_load_dwordx4 v[152:155], v[138:139], off offset:32 sc1
	s_mov_b32 s6, 0xff61b1e6
	v_add_u32_e32 v0, 0x80, v130
	s_waitcnt vmcnt(3)
	v_mov_b32_e32 v138, v134
	s_waitcnt vmcnt(0)
	v_mov_b32_e32 v139, v152
	v_mov_b32_e32 v152, v135
	v_pk_add_f32 v[134:135], v[138:139], v[152:153]
	v_mov_b32_e32 v138, v136
	v_mov_b32_e32 v139, v154
	v_mov_b32_e32 v154, v137
	v_pk_add_f32 v[136:137], v[138:139], v[154:155]
	v_mov_b32_e32 v138, v146
	v_pk_add_f32 v[134:135], v[134:135], v[136:137]
	v_mov_b32_e32 v136, v144
	v_mov_b32_e32 v137, v148
	v_mov_b32_e32 v148, v145
	v_mov_b32_e32 v139, v150
	v_mov_b32_e32 v150, v147
	v_pk_add_f32 v[136:137], v[136:137], v[148:149]
	v_pk_add_f32 v[138:139], v[138:139], v[150:151]
	s_nop 0
	v_pk_add_f32 v[136:137], v[136:137], v[138:139]
	s_nop 0
	v_pk_add_f32 v[134:135], v[134:135], v[136:137]
	s_nop 0
	v_add_f32_e32 v134, v134, v135
	v_fmamk_f32 v134, v134, 0x3a800000, v231
	v_rsq_f32_e32 v134, v134
	s_nop 0
	v_pk_mul_f32 v[64:65], v[64:65], v[134:135] op_sel_hi:[1,0]
	v_pk_mul_f32 v[62:63], v[62:63], v[134:135] op_sel_hi:[1,0]
	v_max_f32_e32 v135, v64, v65
	v_max3_f32 v135, v62, v63, v135
	v_pk_mul_f32 v[60:61], v[60:61], v[134:135] op_sel_hi:[1,0]
	v_pk_mul_f32 v[58:59], v[58:59], v[134:135] op_sel_hi:[1,0]
	v_max_f32_e32 v136, v60, v61
	v_max3_f32 v136, v58, v59, v136
	v_max3_f32 v135, v135, s6, v136
	v_pk_mul_f32 v[56:57], v[56:57], v[134:135] op_sel_hi:[1,0]
	v_pk_mul_f32 v[52:53], v[52:53], v[134:135] op_sel_hi:[1,0]
	v_pk_mul_f32 v[54:55], v[54:55], v[134:135] op_sel_hi:[1,0]
	v_max_f32_e32 v136, v56, v57
	v_pk_mul_f32 v[50:51], v[50:51], v[134:135] op_sel_hi:[1,0]
	v_max_f32_e32 v134, v52, v53
	v_max3_f32 v136, v54, v55, v136
	v_max3_f32 v134, v50, v51, v134
	v_max3_f32 v134, v135, v136, v134
	ds_swizzle_b32 v135, v134 offset:swizzle(SWAP,16)
	s_waitcnt lgkmcnt(0)
	v_max_f32_e32 v135, v135, v135
	v_max_f32_e32 v134, v134, v135
	v_mov_b32_e32 v135, v134
	s_nop 1
	v_permlane32_swap_b32_e32 v134, v135
	s_and_saveexec_b64 s[6:7], s[2:3]
	v_max_f32_e32 v134, v134, v134
	v_max_f32_e32 v135, v135, v135
	v_lshl_add_u32 v136, v0, 4, s9
	v_max_f32_e32 v134, v134, v135
	ds_write_b32 v136, v134
	s_or_b64 exec, exec, s[6:7]
	v_add_co_u32_e32 v134, vcc, 0x2000, v132
	s_mov_b64 s[6:7], 0x2400
	s_nop 0
	v_addc_co_u32_e32 v135, vcc, 0, v133, vcc
	v_lshl_add_u64 v[138:139], v[132:133], 0, s[6:7]
	global_load_dwordx4 v[134:137], v[134:135], off offset:1024 sc1
	s_nop 0
	global_load_dwordx4 v[144:147], v[138:139], off offset:16 sc1
	global_load_dwordx4 v[148:151], v[138:139], off offset:48 sc1
	global_load_dwordx4 v[152:155], v[138:139], off offset:32 sc1
	s_mov_b32 s6, 0xff61b1e6
	v_add_u32_e32 v143, 0x90, v130
	s_waitcnt vmcnt(3)
	v_mov_b32_e32 v138, v134
	s_waitcnt vmcnt(0)
	v_mov_b32_e32 v139, v152
	v_mov_b32_e32 v152, v135
	v_pk_add_f32 v[134:135], v[138:139], v[152:153]
	v_mov_b32_e32 v138, v136
	v_mov_b32_e32 v139, v154
	v_mov_b32_e32 v154, v137
	v_pk_add_f32 v[136:137], v[138:139], v[154:155]
	v_mov_b32_e32 v138, v146
	v_pk_add_f32 v[134:135], v[134:135], v[136:137]
	v_mov_b32_e32 v136, v144
	v_mov_b32_e32 v137, v148
	v_mov_b32_e32 v148, v145
	v_mov_b32_e32 v139, v150
	v_mov_b32_e32 v150, v147
	v_pk_add_f32 v[136:137], v[136:137], v[148:149]
	v_pk_add_f32 v[138:139], v[138:139], v[150:151]
	s_nop 0
	v_pk_add_f32 v[136:137], v[136:137], v[138:139]
	s_nop 0
	v_pk_add_f32 v[134:135], v[134:135], v[136:137]
	s_nop 0
	v_add_f32_e32 v134, v134, v135
	v_fmamk_f32 v134, v134, 0x3a800000, v231
	v_rsq_f32_e32 v134, v134
	s_nop 0
	v_pk_mul_f32 v[48:49], v[48:49], v[134:135] op_sel_hi:[1,0]
	v_pk_mul_f32 v[46:47], v[46:47], v[134:135] op_sel_hi:[1,0]
	v_max_f32_e32 v135, v48, v49
	v_max3_f32 v135, v46, v47, v135
	v_pk_mul_f32 v[44:45], v[44:45], v[134:135] op_sel_hi:[1,0]
	v_pk_mul_f32 v[42:43], v[42:43], v[134:135] op_sel_hi:[1,0]
	v_max_f32_e32 v136, v44, v45
	v_max3_f32 v136, v42, v43, v136
	v_max3_f32 v135, v135, s6, v136
	v_pk_mul_f32 v[40:41], v[40:41], v[134:135] op_sel_hi:[1,0]
	v_pk_mul_f32 v[36:37], v[36:37], v[134:135] op_sel_hi:[1,0]
	v_pk_mul_f32 v[38:39], v[38:39], v[134:135] op_sel_hi:[1,0]
	v_max_f32_e32 v136, v40, v41
	v_pk_mul_f32 v[34:35], v[34:35], v[134:135] op_sel_hi:[1,0]
	v_max_f32_e32 v134, v36, v37
	v_max3_f32 v136, v38, v39, v136
	v_max3_f32 v134, v34, v35, v134
	v_max3_f32 v134, v135, v136, v134
	ds_swizzle_b32 v135, v134 offset:swizzle(SWAP,16)
	s_waitcnt lgkmcnt(0)
	v_max_f32_e32 v135, v135, v135
	v_max_f32_e32 v134, v134, v135
	v_mov_b32_e32 v135, v134
	s_nop 1
	v_permlane32_swap_b32_e32 v134, v135
	s_and_saveexec_b64 s[6:7], s[2:3]
	v_max_f32_e32 v134, v134, v134
	v_max_f32_e32 v135, v135, v135
	v_lshl_add_u32 v136, v143, 4, s9
	v_max_f32_e32 v134, v134, v135
	ds_write_b32 v136, v134
	s_or_b64 exec, exec, s[6:7]
	v_add_co_u32_e32 v134, vcc, 0x2000, v132
	s_mov_b64 s[6:7], 0x2800
	s_nop 0
	v_addc_co_u32_e32 v135, vcc, 0, v133, vcc
	v_lshl_add_u64 v[138:139], v[132:133], 0, s[6:7]
	global_load_dwordx4 v[134:137], v[134:135], off offset:2048 sc1
	s_nop 0
	global_load_dwordx4 v[144:147], v[138:139], off offset:16 sc1
	global_load_dwordx4 v[148:151], v[138:139], off offset:48 sc1
	global_load_dwordx4 v[152:155], v[138:139], off offset:32 sc1
	s_mov_b32 s6, 0xff61b1e6
	s_waitcnt vmcnt(3)
	v_mov_b32_e32 v138, v134
	s_waitcnt vmcnt(0)
	v_mov_b32_e32 v139, v152
	v_mov_b32_e32 v152, v135
	v_pk_add_f32 v[134:135], v[138:139], v[152:153]
	v_mov_b32_e32 v138, v136
	v_mov_b32_e32 v139, v154
	v_mov_b32_e32 v154, v137
	v_pk_add_f32 v[136:137], v[138:139], v[154:155]
	v_mov_b32_e32 v138, v146
	v_pk_add_f32 v[134:135], v[134:135], v[136:137]
	v_mov_b32_e32 v136, v144
	v_mov_b32_e32 v137, v148
	v_mov_b32_e32 v148, v145
	v_mov_b32_e32 v139, v150
	v_mov_b32_e32 v150, v147
	v_pk_add_f32 v[136:137], v[136:137], v[148:149]
	v_pk_add_f32 v[138:139], v[138:139], v[150:151]
	v_add_u32_e32 v144, 0xa0, v130
	v_pk_add_f32 v[136:137], v[136:137], v[138:139]
	s_nop 0
	v_pk_add_f32 v[134:135], v[134:135], v[136:137]
	s_nop 0
	v_add_f32_e32 v134, v134, v135
	v_fmamk_f32 v134, v134, 0x3a800000, v231
	v_rsq_f32_e32 v134, v134
	s_nop 0
	v_pk_mul_f32 v[32:33], v[32:33], v[134:135] op_sel_hi:[1,0]
	v_pk_mul_f32 v[30:31], v[30:31], v[134:135] op_sel_hi:[1,0]
	v_max_f32_e32 v135, v32, v33
	v_max3_f32 v135, v30, v31, v135
	v_pk_mul_f32 v[28:29], v[28:29], v[134:135] op_sel_hi:[1,0]
	v_pk_mul_f32 v[26:27], v[26:27], v[134:135] op_sel_hi:[1,0]
	v_max_f32_e32 v136, v28, v29
	v_max3_f32 v136, v26, v27, v136
	v_max3_f32 v135, v135, s6, v136
	v_pk_mul_f32 v[24:25], v[24:25], v[134:135] op_sel_hi:[1,0]
	v_pk_mul_f32 v[20:21], v[20:21], v[134:135] op_sel_hi:[1,0]
	v_pk_mul_f32 v[22:23], v[22:23], v[134:135] op_sel_hi:[1,0]
	v_max_f32_e32 v136, v24, v25
	v_pk_mul_f32 v[18:19], v[18:19], v[134:135] op_sel_hi:[1,0]
	v_max_f32_e32 v134, v20, v21
	v_max3_f32 v136, v22, v23, v136
	v_max3_f32 v134, v18, v19, v134
	v_max3_f32 v134, v135, v136, v134
	ds_swizzle_b32 v135, v134 offset:swizzle(SWAP,16)
	s_waitcnt lgkmcnt(0)
	v_max_f32_e32 v135, v135, v135
	v_max_f32_e32 v134, v134, v135
	v_mov_b32_e32 v135, v134
	s_nop 1
	v_permlane32_swap_b32_e32 v134, v135
	s_and_saveexec_b64 s[6:7], s[2:3]
	v_max_f32_e32 v134, v134, v134
	v_max_f32_e32 v135, v135, v135
	v_lshl_add_u32 v136, v144, 4, s9
	v_max_f32_e32 v134, v134, v135
	ds_write_b32 v136, v134
	s_or_b64 exec, exec, s[6:7]
	s_mov_b64 s[6:7], 0x2c00
	v_lshl_add_u64 v[150:151], v[132:133], 0, s[6:7]
	v_add_co_u32_e32 v132, vcc, 0x2000, v132
	s_mov_b32 s6, 0xff61b1e6
	s_nop 0
	v_addc_co_u32_e32 v133, vcc, 0, v133, vcc
	global_load_dwordx4 v[132:135], v[132:133], off offset:3072 sc1
	s_nop 0
	global_load_dwordx4 v[136:139], v[150:151], off offset:16 sc1
	global_load_dwordx4 v[146:149], v[150:151], off offset:48 sc1
	s_nop 0
	global_load_dwordx4 v[150:153], v[150:151], off offset:32 sc1
	v_add_u32_e32 v145, 0xb0, v130
	s_waitcnt vmcnt(3)
	v_mov_b32_e32 v154, v132
	s_waitcnt vmcnt(0)
	v_mov_b32_e32 v155, v150
	v_mov_b32_e32 v150, v133
	v_pk_add_f32 v[132:133], v[154:155], v[150:151]
	v_mov_b32_e32 v150, v134
	v_mov_b32_e32 v151, v152
	v_mov_b32_e32 v152, v135
	v_pk_add_f32 v[134:135], v[150:151], v[152:153]
	s_nop 0
	v_pk_add_f32 v[132:133], v[132:133], v[134:135]
	v_mov_b32_e32 v134, v136
	v_mov_b32_e32 v135, v146
	v_mov_b32_e32 v146, v137
	v_mov_b32_e32 v136, v138
	v_mov_b32_e32 v137, v148
	v_mov_b32_e32 v148, v139
	v_pk_add_f32 v[134:135], v[134:135], v[146:147]
	v_pk_add_f32 v[136:137], v[136:137], v[148:149]
	s_nop 0
	v_pk_add_f32 v[134:135], v[134:135], v[136:137]
	s_nop 0
	v_pk_add_f32 v[132:133], v[132:133], v[134:135]
	s_nop 0
	v_add_f32_e32 v132, v132, v133
	v_fmamk_f32 v132, v132, 0x3a800000, v231
	v_rsq_f32_e32 v134, v132
	s_nop 0
	v_pk_mul_f32 v[16:17], v[16:17], v[134:135] op_sel_hi:[1,0]
	v_pk_mul_f32 v[14:15], v[14:15], v[134:135] op_sel_hi:[1,0]
	v_max_f32_e32 v132, v16, v17
	v_max3_f32 v135, v14, v15, v132
	v_pk_mul_f32 v[132:133], v[12:13], v[134:135] op_sel_hi:[1,0]
	v_pk_mul_f32 v[12:13], v[10:11], v[134:135] op_sel_hi:[1,0]
	v_max_f32_e32 v10, v132, v133
	v_max3_f32 v10, v12, v13, v10
	v_pk_mul_f32 v[136:137], v[8:9], v[134:135] op_sel_hi:[1,0]
	v_pk_mul_f32 v[138:139], v[4:5], v[134:135] op_sel_hi:[1,0]
	v_max3_f32 v10, v135, s6, v10
	v_pk_mul_f32 v[8:9], v[6:7], v[134:135] op_sel_hi:[1,0]
	v_max_f32_e32 v6, v136, v137
	v_pk_mul_f32 v[134:135], v[2:3], v[134:135] op_sel_hi:[1,0]
	v_max_f32_e32 v2, v138, v139
	v_max3_f32 v6, v8, v9, v6
	v_max3_f32 v2, v134, v135, v2
	v_max3_f32 v2, v10, v6, v2
	ds_swizzle_b32 v3, v2 offset:swizzle(SWAP,16)
	s_waitcnt lgkmcnt(0)
	v_max_f32_e32 v3, v3, v3
	v_max_f32_e32 v2, v2, v3
	v_mov_b32_e32 v3, v2
	s_nop 1
	v_permlane32_swap_b32_e32 v2, v3
	s_and_saveexec_b64 s[6:7], s[2:3]
	v_max_f32_e32 v2, v2, v2
	v_max_f32_e32 v3, v3, v3
	v_lshl_add_u32 v4, v145, 4, s9
	v_max_f32_e32 v2, v2, v3
	ds_write_b32 v4, v2
	s_or_b64 exec, exec, s[6:7]
	v_lshl_add_u32 v2, v130, 4, 0
	s_waitcnt lgkmcnt(0)
	s_barrier
	v_add_u32_e32 v2, 0x20000, v2
	ds_read_b128 v[4:7], v2
	s_add_i32 s8, s8, 0x21000
	s_waitcnt lgkmcnt(0)
	v_max_f32_e32 v3, v7, v7
	v_max_f32_e32 v6, v6, v6
	v_max_f32_e32 v3, v6, v3
	v_max3_f32 v3, v4, v5, v3
	v_sub_f32_e32 v4, v129, v3
	v_sub_f32_e32 v5, v128, v3
	v_sub_f32_e32 v6, v127, v3
	v_sub_f32_e32 v7, v126, v3
	v_exp_f32_e32 v126, v7
	v_exp_f32_e32 v127, v6
	v_exp_f32_e32 v128, v5
	v_exp_f32_e32 v129, v4
	v_sub_f32_e32 v6, v125, v3
	v_sub_f32_e32 v7, v124, v3
	v_sub_f32_e32 v10, v123, v3
	v_sub_f32_e32 v11, v122, v3
	v_exp_f32_e32 v122, v11
	v_exp_f32_e32 v123, v10
	v_exp_f32_e32 v124, v7
	v_exp_f32_e32 v125, v6
	v_sub_f32_e32 v7, v121, v3
	v_sub_f32_e32 v10, v120, v3
	v_sub_f32_e32 v11, v119, v3
	v_sub_f32_e32 v118, v118, v3
	v_exp_f32_e32 v118, v118
	v_exp_f32_e32 v119, v11
	v_exp_f32_e32 v120, v10
	v_exp_f32_e32 v121, v7
	v_add_f32_e32 v4, v126, v127
	v_add_f32_e32 v5, v128, v129
	v_sub_f32_e32 v7, v117, v3
	v_sub_f32_e32 v10, v116, v3
	v_sub_f32_e32 v11, v115, v3
	v_sub_f32_e32 v3, v114, v3
	v_add_f32_e32 v4, v4, v5
	v_add_f32_e32 v5, v122, v123
	v_add_f32_e32 v6, v124, v125
	v_exp_f32_e32 v114, v3
	v_exp_f32_e32 v115, v11
	v_exp_f32_e32 v116, v10
	v_exp_f32_e32 v117, v7
	v_add_f32_e32 v4, 0, v4
	v_add_f32_e32 v5, v5, v6
	v_add_f32_e32 v4, v5, v4
	v_add_f32_e32 v5, v118, v119
	v_add_f32_e32 v6, v120, v121
	v_add_f32_e32 v3, v5, v6
	v_add_f32_e32 v3, v3, v4
	v_add_f32_e32 v4, v114, v115
	v_add_f32_e32 v5, v116, v117
	v_add_f32_e32 v4, v4, v5
	v_add_f32_e32 v3, v4, v3
	ds_swizzle_b32 v4, v3 offset:swizzle(SWAP,16)
	v_lshlrev_b32_e32 v5, 2, v130
	v_lshl_add_u32 v146, v5, 2, s8
	s_waitcnt lgkmcnt(0)
	v_add_f32_e32 v3, v3, v4
	v_mov_b32_e32 v4, v3
	s_nop 1
	v_permlane32_swap_b32_e32 v3, v4
	s_and_saveexec_b64 s[6:7], s[2:3]
	v_add_f32_e32 v3, v3, v4
	ds_write_b32 v146, v3
	s_or_b64 exec, exec, s[6:7]
	ds_read_b128 v[4:7], v2 offset:256
	s_waitcnt lgkmcnt(0)
	v_max_f32_e32 v3, v7, v7
	v_max_f32_e32 v6, v6, v6
	v_max_f32_e32 v3, v6, v3
	v_max3_f32 v3, v4, v5, v3
	v_sub_f32_e32 v4, v113, v3
	v_sub_f32_e32 v5, v112, v3
	v_sub_f32_e32 v6, v111, v3
	v_sub_f32_e32 v7, v110, v3
	v_exp_f32_e32 v110, v7
	v_exp_f32_e32 v111, v6
	v_exp_f32_e32 v112, v5
	v_exp_f32_e32 v113, v4
	v_sub_f32_e32 v6, v109, v3
	v_sub_f32_e32 v7, v108, v3
	v_sub_f32_e32 v10, v107, v3
	v_sub_f32_e32 v11, v106, v3
	v_exp_f32_e32 v106, v11
	v_exp_f32_e32 v107, v10
	v_exp_f32_e32 v108, v7
	v_exp_f32_e32 v109, v6
	v_sub_f32_e32 v7, v105, v3
	v_sub_f32_e32 v10, v104, v3
	v_sub_f32_e32 v11, v103, v3
	v_sub_f32_e32 v102, v102, v3
	v_exp_f32_e32 v102, v102
	v_exp_f32_e32 v103, v11
	v_exp_f32_e32 v104, v10
	v_exp_f32_e32 v105, v7
	v_add_f32_e32 v4, v110, v111
	v_add_f32_e32 v5, v112, v113
	v_sub_f32_e32 v7, v101, v3
	v_sub_f32_e32 v10, v100, v3
	v_sub_f32_e32 v11, v99, v3
	v_sub_f32_e32 v3, v98, v3
	v_add_f32_e32 v4, v4, v5
	v_add_f32_e32 v5, v106, v107
	v_add_f32_e32 v6, v108, v109
	v_exp_f32_e32 v98, v3
	v_exp_f32_e32 v99, v11
	v_exp_f32_e32 v100, v10
	v_exp_f32_e32 v101, v7
	v_add_f32_e32 v4, 0, v4
	v_add_f32_e32 v5, v5, v6
	v_add_f32_e32 v4, v5, v4
	v_add_f32_e32 v5, v102, v103
	v_add_f32_e32 v6, v104, v105
	v_add_f32_e32 v3, v5, v6
	v_add_f32_e32 v3, v3, v4
	v_add_f32_e32 v4, v98, v99
	v_add_f32_e32 v5, v100, v101
	v_add_f32_e32 v4, v4, v5
	v_add_f32_e32 v3, v4, v3
	ds_swizzle_b32 v4, v3 offset:swizzle(SWAP,16)
	s_waitcnt lgkmcnt(0)
	v_add_f32_e32 v3, v3, v4
	v_mov_b32_e32 v4, v3
	s_nop 1
	v_permlane32_swap_b32_e32 v3, v4
	s_and_saveexec_b64 s[6:7], s[2:3]
	v_add_f32_e32 v3, v3, v4
	ds_write_b32 v146, v3 offset:256
	s_or_b64 exec, exec, s[6:7]
	v_mad_u64_u32 v[4:5], s[6:7], v130, 3, v[0:1]
	v_lshl_add_u32 v3, v4, 2, 0
	v_add_u32_e32 v3, 0x20000, v3
	ds_read_b128 v[4:7], v3
	s_waitcnt lgkmcnt(0)
	v_max_f32_e32 v3, v7, v7
	v_max_f32_e32 v6, v6, v6
	v_max_f32_e32 v3, v6, v3
	v_max3_f32 v3, v4, v5, v3
	v_sub_f32_e32 v4, v97, v3
	v_sub_f32_e32 v5, v96, v3
	v_sub_f32_e32 v6, v95, v3
	v_sub_f32_e32 v7, v94, v3
	v_exp_f32_e32 v94, v7
	v_exp_f32_e32 v95, v6
	v_exp_f32_e32 v96, v5
	v_exp_f32_e32 v97, v4
	v_sub_f32_e32 v6, v93, v3
	v_sub_f32_e32 v7, v92, v3
	v_sub_f32_e32 v10, v91, v3
	v_sub_f32_e32 v11, v90, v3
	v_exp_f32_e32 v90, v11
	v_exp_f32_e32 v91, v10
	v_exp_f32_e32 v92, v7
	v_exp_f32_e32 v93, v6
	v_sub_f32_e32 v7, v89, v3
	v_sub_f32_e32 v10, v88, v3
	v_sub_f32_e32 v11, v87, v3
	v_sub_f32_e32 v86, v86, v3
	v_exp_f32_e32 v86, v86
	v_exp_f32_e32 v87, v11
	v_exp_f32_e32 v88, v10
	v_exp_f32_e32 v89, v7
	v_add_f32_e32 v4, v94, v95
	v_add_f32_e32 v5, v96, v97
	v_sub_f32_e32 v7, v85, v3
	v_sub_f32_e32 v10, v84, v3
	v_sub_f32_e32 v11, v83, v3
	v_sub_f32_e32 v3, v82, v3
	v_add_f32_e32 v4, v4, v5
	v_add_f32_e32 v5, v90, v91
	v_add_f32_e32 v6, v92, v93
	v_exp_f32_e32 v82, v3
	v_exp_f32_e32 v83, v11
	v_exp_f32_e32 v84, v10
	v_exp_f32_e32 v85, v7
	v_add_f32_e32 v4, 0, v4
	v_add_f32_e32 v5, v5, v6
	v_add_f32_e32 v4, v5, v4
	v_add_f32_e32 v5, v86, v87
	v_add_f32_e32 v6, v88, v89
	v_add_f32_e32 v3, v5, v6
	v_add_f32_e32 v3, v3, v4
	v_add_f32_e32 v4, v82, v83
	v_add_f32_e32 v5, v84, v85
	v_add_f32_e32 v4, v4, v5
	v_add_f32_e32 v3, v4, v3
	ds_swizzle_b32 v4, v3 offset:swizzle(SWAP,16)
	s_waitcnt lgkmcnt(0)
	v_add_f32_e32 v3, v3, v4
	v_mov_b32_e32 v4, v3
	s_nop 1
	v_permlane32_swap_b32_e32 v3, v4
	s_and_saveexec_b64 s[6:7], s[2:3]
	v_add_f32_e32 v3, v3, v4
	ds_write_b32 v146, v3 offset:512
	s_or_b64 exec, exec, s[6:7]
	ds_read_b128 v[4:7], v2 offset:768
	s_waitcnt lgkmcnt(0)
	v_max_f32_e32 v3, v7, v7
	v_max_f32_e32 v6, v6, v6
	v_max_f32_e32 v3, v6, v3
	v_max3_f32 v3, v4, v5, v3
	v_sub_f32_e32 v4, v81, v3
	v_sub_f32_e32 v5, v80, v3
	v_sub_f32_e32 v6, v79, v3
	v_sub_f32_e32 v7, v78, v3
	v_exp_f32_e32 v78, v7
	v_exp_f32_e32 v79, v6
	v_exp_f32_e32 v80, v5
	v_exp_f32_e32 v81, v4
	v_sub_f32_e32 v6, v77, v3
	v_sub_f32_e32 v7, v76, v3
	v_sub_f32_e32 v10, v75, v3
	v_sub_f32_e32 v11, v74, v3
	v_exp_f32_e32 v74, v11
	v_exp_f32_e32 v75, v10
	v_exp_f32_e32 v76, v7
	v_exp_f32_e32 v77, v6
	v_sub_f32_e32 v7, v73, v3
	v_sub_f32_e32 v10, v72, v3
	v_sub_f32_e32 v11, v71, v3
	v_sub_f32_e32 v70, v70, v3
	v_exp_f32_e32 v70, v70
	v_exp_f32_e32 v71, v11
	v_exp_f32_e32 v72, v10
	v_exp_f32_e32 v73, v7
	v_add_f32_e32 v4, v78, v79
	v_add_f32_e32 v5, v80, v81
	v_sub_f32_e32 v7, v69, v3
	v_sub_f32_e32 v10, v68, v3
	v_sub_f32_e32 v11, v67, v3
	v_sub_f32_e32 v3, v66, v3
	v_add_f32_e32 v4, v4, v5
	v_add_f32_e32 v5, v74, v75
	v_add_f32_e32 v6, v76, v77
	v_exp_f32_e32 v66, v3
	v_exp_f32_e32 v67, v11
	v_exp_f32_e32 v68, v10
	v_exp_f32_e32 v69, v7
	v_add_f32_e32 v4, 0, v4
	v_add_f32_e32 v5, v5, v6
	v_add_f32_e32 v4, v5, v4
	v_add_f32_e32 v5, v70, v71
	v_add_f32_e32 v6, v72, v73
	v_add_f32_e32 v3, v5, v6
	v_add_f32_e32 v3, v3, v4
	v_add_f32_e32 v4, v66, v67
	v_add_f32_e32 v5, v68, v69
	v_add_f32_e32 v4, v4, v5
	v_add_f32_e32 v3, v4, v3
	ds_swizzle_b32 v4, v3 offset:swizzle(SWAP,16)
	s_waitcnt lgkmcnt(0)
	v_add_f32_e32 v3, v3, v4
	v_mov_b32_e32 v4, v3
	s_nop 1
	v_permlane32_swap_b32_e32 v3, v4
	s_and_saveexec_b64 s[6:7], s[2:3]
	v_add_f32_e32 v3, v3, v4
	ds_write_b32 v146, v3 offset:768
	s_or_b64 exec, exec, s[6:7]
	ds_read_b128 v[4:7], v2 offset:2048
	s_waitcnt lgkmcnt(0)
	v_max_f32_e32 v3, v7, v7
	v_max_f32_e32 v6, v6, v6
	v_max_f32_e32 v3, v6, v3
	v_max3_f32 v3, v4, v5, v3
	v_sub_f32_e32 v4, v65, v3
	v_sub_f32_e32 v5, v64, v3
	v_sub_f32_e32 v6, v63, v3
	v_sub_f32_e32 v7, v62, v3
	v_exp_f32_e32 v62, v7
	v_exp_f32_e32 v63, v6
	v_exp_f32_e32 v64, v5
	v_exp_f32_e32 v65, v4
	v_sub_f32_e32 v6, v61, v3
	v_sub_f32_e32 v7, v60, v3
	v_sub_f32_e32 v10, v59, v3
	v_sub_f32_e32 v11, v58, v3
	v_exp_f32_e32 v58, v11
	v_exp_f32_e32 v59, v10
	v_exp_f32_e32 v60, v7
	v_exp_f32_e32 v61, v6
	v_sub_f32_e32 v7, v57, v3
	v_sub_f32_e32 v56, v56, v3
	v_sub_f32_e32 v11, v55, v3
	v_sub_f32_e32 v10, v54, v3
	v_exp_f32_e32 v10, v10
	v_exp_f32_e32 v11, v11
	v_exp_f32_e32 v54, v56
	v_exp_f32_e32 v55, v7
	v_add_f32_e32 v4, v62, v63
	v_add_f32_e32 v5, v64, v65
	v_sub_f32_e32 v7, v53, v3
	v_sub_f32_e32 v52, v52, v3
	v_sub_f32_e32 v51, v51, v3
	v_sub_f32_e32 v3, v50, v3
	v_add_f32_e32 v4, v4, v5
	v_add_f32_e32 v5, v58, v59
	v_add_f32_e32 v6, v60, v61
	v_exp_f32_e32 v50, v3
	v_exp_f32_e32 v51, v51
	v_exp_f32_e32 v52, v52
	v_exp_f32_e32 v53, v7
	v_add_f32_e32 v4, 0, v4
	v_add_f32_e32 v5, v5, v6
	v_add_f32_e32 v4, v5, v4
	v_add_f32_e32 v5, v10, v11
	v_add_f32_e32 v6, v54, v55
	v_add_f32_e32 v3, v5, v6
	v_add_f32_e32 v3, v3, v4
	v_add_f32_e32 v4, v50, v51
	v_add_f32_e32 v5, v52, v53
	v_add_f32_e32 v4, v4, v5
	v_add_f32_e32 v3, v4, v3
	ds_swizzle_b32 v4, v3 offset:swizzle(SWAP,16)
	s_waitcnt lgkmcnt(0)
	v_add_f32_e32 v3, v3, v4
	v_mov_b32_e32 v4, v3
	s_nop 1
	v_permlane32_swap_b32_e32 v3, v4
	s_and_saveexec_b64 s[6:7], s[2:3]
	v_add_f32_e32 v3, v3, v4
	ds_write_b32 v146, v3 offset:2048
	s_or_b64 exec, exec, s[6:7]
	ds_read_b128 v[4:7], v2 offset:2304
	s_waitcnt lgkmcnt(0)
	v_max_f32_e32 v3, v7, v7
	v_max_f32_e32 v6, v6, v6
	v_max_f32_e32 v3, v6, v3
	v_max3_f32 v3, v4, v5, v3
	v_sub_f32_e32 v4, v49, v3
	v_sub_f32_e32 v5, v48, v3
	v_sub_f32_e32 v6, v47, v3
	v_sub_f32_e32 v7, v46, v3
	v_exp_f32_e32 v46, v7
	v_exp_f32_e32 v47, v6
	v_exp_f32_e32 v48, v5
	v_exp_f32_e32 v49, v4
	v_sub_f32_e32 v6, v45, v3
	v_sub_f32_e32 v7, v44, v3
	v_sub_f32_e32 v43, v43, v3
	v_sub_f32_e32 v42, v42, v3
	v_exp_f32_e32 v42, v42
	v_exp_f32_e32 v43, v43
	v_exp_f32_e32 v56, v7
	v_exp_f32_e32 v57, v6
	v_sub_f32_e32 v41, v41, v3
	v_sub_f32_e32 v40, v40, v3
	v_sub_f32_e32 v7, v39, v3
	v_sub_f32_e32 v6, v38, v3
	v_exp_f32_e32 v6, v6
	v_exp_f32_e32 v7, v7
	v_exp_f32_e32 v38, v40
	v_exp_f32_e32 v39, v41
	v_add_f32_e32 v4, v46, v47
	v_add_f32_e32 v5, v48, v49
	v_sub_f32_e32 v37, v37, v3
	v_sub_f32_e32 v36, v36, v3
	v_sub_f32_e32 v35, v35, v3
	v_sub_f32_e32 v3, v34, v3
	v_add_f32_e32 v4, v4, v5
	v_add_f32_e32 v5, v42, v43
	v_add_f32_e32 v44, v56, v57
	v_exp_f32_e32 v34, v3
	v_exp_f32_e32 v35, v35
	v_exp_f32_e32 v36, v36
	v_exp_f32_e32 v37, v37
	v_add_f32_e32 v4, 0, v4
	v_add_f32_e32 v5, v5, v44
	v_add_f32_e32 v4, v5, v4
	v_add_f32_e32 v5, v6, v7
	v_add_f32_e32 v40, v38, v39
	v_add_f32_e32 v3, v5, v40
	v_add_f32_e32 v3, v3, v4
	v_add_f32_e32 v4, v34, v35
	v_add_f32_e32 v5, v36, v37
	v_add_f32_e32 v4, v4, v5
	v_add_f32_e32 v3, v4, v3
	ds_swizzle_b32 v4, v3 offset:swizzle(SWAP,16)
	s_waitcnt lgkmcnt(0)
	v_add_f32_e32 v3, v3, v4
	v_mov_b32_e32 v4, v3
	s_nop 1
	v_permlane32_swap_b32_e32 v3, v4
	s_and_saveexec_b64 s[6:7], s[2:3]
	v_add_f32_e32 v3, v3, v4
	ds_write_b32 v146, v3 offset:2304
	s_or_b64 exec, exec, s[6:7]
	ds_read_b128 v[148:151], v2 offset:2560
	s_waitcnt lgkmcnt(0)
	v_max_f32_e32 v3, v151, v151
	v_max_f32_e32 v4, v150, v150
	v_max_f32_e32 v3, v4, v3
	v_max3_f32 v3, v148, v149, v3
	v_sub_f32_e32 v4, v33, v3
	v_sub_f32_e32 v5, v32, v3
	v_sub_f32_e32 v31, v31, v3
	v_sub_f32_e32 v30, v30, v3
	v_exp_f32_e32 v30, v30
	v_exp_f32_e32 v31, v31
	v_exp_f32_e32 v32, v5
	v_exp_f32_e32 v33, v4
	v_sub_f32_e32 v40, v29, v3
	v_sub_f32_e32 v41, v28, v3
	v_sub_f32_e32 v27, v27, v3
	v_sub_f32_e32 v26, v26, v3
	v_exp_f32_e32 v28, v26
	v_exp_f32_e32 v29, v27
	v_exp_f32_e32 v44, v41
	v_exp_f32_e32 v45, v40
	v_add_f32_e32 v4, v30, v31
	v_add_f32_e32 v5, v32, v33
	v_add_f32_e32 v4, v4, v5
	v_add_f32_e32 v26, 0, v4
	v_add_f32_e32 v27, v28, v29
	v_add_f32_e32 v40, v44, v45
	v_sub_f32_e32 v25, v25, v3
	v_sub_f32_e32 v24, v24, v3
	v_sub_f32_e32 v5, v23, v3
	v_sub_f32_e32 v4, v22, v3
	v_exp_f32_e32 v4, v4
	v_exp_f32_e32 v5, v5
	v_exp_f32_e32 v22, v24
	v_exp_f32_e32 v23, v25
	v_add_f32_e32 v24, v27, v40
	v_sub_f32_e32 v21, v21, v3
	v_sub_f32_e32 v20, v20, v3
	v_sub_f32_e32 v19, v19, v3
	v_sub_f32_e32 v3, v18, v3
	v_add_f32_e32 v24, v24, v26
	v_exp_f32_e32 v18, v3
	v_exp_f32_e32 v19, v19
	v_exp_f32_e32 v26, v20
	v_exp_f32_e32 v27, v21
	v_add_f32_e32 v25, v4, v5
	v_add_f32_e32 v40, v22, v23
	v_add_f32_e32 v3, v25, v40
	v_add_f32_e32 v20, v18, v19
	v_add_f32_e32 v21, v26, v27
	v_add_f32_e32 v3, v3, v24
	v_add_f32_e32 v20, v20, v21
	v_add_f32_e32 v3, v20, v3
	ds_swizzle_b32 v20, v3 offset:swizzle(SWAP,16)
	s_waitcnt lgkmcnt(0)
	v_add_f32_e32 v3, v3, v20
	v_mov_b32_e32 v20, v3
	s_nop 1
	v_permlane32_swap_b32_e32 v3, v20
	s_and_saveexec_b64 s[6:7], s[2:3]
	v_add_f32_e32 v3, v3, v20
	ds_write_b32 v146, v3 offset:2560
	s_or_b64 exec, exec, s[6:7]
	ds_read_b128 v[148:151], v2 offset:2816
	s_waitcnt lgkmcnt(0)
	v_max_f32_e32 v2, v151, v151
	v_max_f32_e32 v3, v150, v150
	v_max_f32_e32 v2, v3, v2
	v_max3_f32 v147, v148, v149, v2
	v_sub_f32_e32 v2, v17, v147
	v_sub_f32_e32 v3, v16, v147
	v_sub_f32_e32 v15, v15, v147
	v_sub_f32_e32 v14, v14, v147
	v_exp_f32_e32 v14, v14
	v_exp_f32_e32 v15, v15
	v_exp_f32_e32 v20, v3
	v_exp_f32_e32 v21, v2
	v_sub_f32_e32 v16, v133, v147
	v_sub_f32_e32 v17, v132, v147
	v_sub_f32_e32 v13, v13, v147
	v_sub_f32_e32 v12, v12, v147
	v_exp_f32_e32 v24, v12
	v_exp_f32_e32 v25, v13
	v_exp_f32_e32 v40, v17
	v_exp_f32_e32 v41, v16
	v_add_f32_e32 v2, v14, v15
	v_add_f32_e32 v3, v20, v21
	v_add_f32_e32 v2, v2, v3
	v_add_f32_e32 v12, 0, v2
	v_add_f32_e32 v13, v24, v25
	v_add_f32_e32 v16, v40, v41
	v_sub_f32_e32 v17, v137, v147
	v_sub_f32_e32 v132, v136, v147
	v_sub_f32_e32 v3, v9, v147
	v_sub_f32_e32 v2, v8, v147
	v_exp_f32_e32 v2, v2
	v_exp_f32_e32 v3, v3
	v_exp_f32_e32 v8, v132
	v_exp_f32_e32 v9, v17
	v_add_f32_e32 v13, v13, v16
	v_add_f32_e32 v132, v13, v12
	v_sub_f32_e32 v17, v139, v147
	v_sub_f32_e32 v16, v138, v147
	v_sub_f32_e32 v13, v135, v147
	v_sub_f32_e32 v12, v134, v147
	v_exp_f32_e32 v12, v12
	v_exp_f32_e32 v13, v13
	v_exp_f32_e32 v16, v16
	v_exp_f32_e32 v17, v17
	v_add_f32_e32 v133, v2, v3
	v_add_f32_e32 v136, v8, v9
	v_add_f32_e32 v133, v133, v136
	v_add_f32_e32 v132, v133, v132
	v_add_f32_e32 v133, v12, v13
	v_add_f32_e32 v134, v16, v17
	v_add_f32_e32 v133, v133, v134
	v_add_f32_e32 v132, v133, v132
	ds_swizzle_b32 v133, v132 offset:swizzle(SWAP,16)
	s_waitcnt lgkmcnt(0)
	v_add_f32_e32 v132, v132, v133
	v_mov_b32_e32 v133, v132
	s_nop 1
	v_permlane32_swap_b32_e32 v132, v133
	s_and_saveexec_b64 s[6:7], s[2:3]
	v_add_f32_e32 v132, v132, v133
	ds_write_b32 v146, v132 offset:2816
	s_or_b64 exec, exec, s[6:7]
	s_lshl_b32 s2, s16, 5
	s_or_b32 s3, s15, s2
	s_mul_i32 s6, s14, 0x180000
	s_mul_hi_i32 s2, s14, 0x180000
	s_add_u32 s4, s4, s6
	s_addc_u32 s5, s5, s2
	s_add_i32 s2, 0, 0x21000
	s_waitcnt lgkmcnt(0)
	s_barrier
	v_lshl_add_u32 v132, v130, 4, s2
	ds_read_b128 v[132:135], v132
	v_lshl_add_u32 v136, v131, 3, s3
	v_ashrrev_i32_e32 v131, 31, v130
	v_lshlrev_b64 v[130:131], 11, v[130:131]
	v_lshl_add_u64 v[130:131], s[4:5], 0, v[130:131]
	s_waitcnt lgkmcnt(0)
	v_mov_b32_e32 v138, v133
	v_mov_b32_e32 v139, v134
	v_mov_b32_e32 v133, v135
	v_pk_add_f32 v[132:133], v[138:139], v[132:133]
	v_ashrrev_i32_e32 v137, 31, v136
	v_add_f32_e32 v132, v132, v133
	v_rcp_f32_e32 v132, v132
	v_lshl_add_u64 v[130:131], v[136:137], 1, v[130:131]
	s_mov_b32 s3, 0x9800000
	s_mov_b64 s[4:5], 0x9800000
	v_pk_mul_f32 v[126:127], v[126:127], v[132:133] op_sel_hi:[1,0]
	v_pk_mul_f32 v[134:135], v[124:125], v[132:133] op_sel_hi:[1,0]
	v_pk_mul_f32 v[124:125], v[122:123], v[132:133] op_sel_hi:[1,0]
	v_cvt_pk_bf16_f32 v122, v126, v127
	v_add_co_u32_e32 v126, vcc, s3, v130
	v_pk_mul_f32 v[128:129], v[128:129], v[132:133] op_sel_hi:[1,0]
	s_nop 0
	v_addc_co_u32_e32 v127, vcc, 0, v131, vcc
	v_cvt_pk_bf16_f32 v123, v128, v129
	v_pk_mul_f32 v[118:119], v[118:119], v[132:133] op_sel_hi:[1,0]
	v_cvt_pk_bf16_f32 v124, v124, v125
	v_cvt_pk_bf16_f32 v125, v134, v135
	global_store_dwordx4 v[126:127], v[122:125], off
	v_pk_mul_f32 v[120:121], v[120:121], v[132:133] op_sel_hi:[1,0]
	s_mov_b32 s3, 0x9808000
	v_pk_mul_f32 v[122:123], v[116:117], v[132:133] op_sel_hi:[1,0]
	v_pk_mul_f32 v[116:117], v[114:115], v[132:133] op_sel_hi:[1,0]
	v_cvt_pk_bf16_f32 v114, v118, v119
	v_lshl_add_u32 v118, v140, 4, s2
	v_cvt_pk_bf16_f32 v115, v120, v121
	v_cvt_pk_bf16_f32 v116, v116, v117
	v_cvt_pk_bf16_f32 v117, v122, v123
	ds_read_b128 v[118:121], v118
	v_lshl_add_u32 v0, v0, 4, s2
	s_waitcnt lgkmcnt(0)
	v_mov_b32_e32 v122, v119
	v_mov_b32_e32 v123, v120
	v_mov_b32_e32 v119, v121
	v_pk_add_f32 v[118:119], v[122:123], v[118:119]
	v_lshl_add_u64 v[120:121], v[130:131], 0, s[4:5]
	v_add_f32_e32 v118, v118, v119
	v_rcp_f32_e32 v118, v118
	global_store_dwordx4 v[120:121], v[114:117], off offset:256
	v_pk_mul_f32 v[110:111], v[110:111], v[118:119] op_sel_hi:[1,0]
	s_nop 0
	v_pk_mul_f32 v[114:115], v[108:109], v[118:119] op_sel_hi:[1,0]
	v_pk_mul_f32 v[108:109], v[106:107], v[118:119] op_sel_hi:[1,0]
	v_cvt_pk_bf16_f32 v106, v110, v111
	v_add_co_u32_e32 v110, vcc, s3, v130
	v_pk_mul_f32 v[112:113], v[112:113], v[118:119] op_sel_hi:[1,0]
	s_nop 0
	v_addc_co_u32_e32 v111, vcc, 0, v131, vcc
	v_cvt_pk_bf16_f32 v107, v112, v113
	v_pk_mul_f32 v[102:103], v[102:103], v[118:119] op_sel_hi:[1,0]
	v_cvt_pk_bf16_f32 v108, v108, v109
	v_cvt_pk_bf16_f32 v109, v114, v115
	global_store_dwordx4 v[110:111], v[106:109], off
	v_pk_mul_f32 v[104:105], v[104:105], v[118:119] op_sel_hi:[1,0]
	s_mov_b32 s3, 0x9810000
	v_pk_mul_f32 v[106:107], v[100:101], v[118:119] op_sel_hi:[1,0]
	v_pk_mul_f32 v[100:101], v[98:99], v[118:119] op_sel_hi:[1,0]
	v_cvt_pk_bf16_f32 v98, v102, v103
	v_lshl_add_u32 v102, v141, 4, s2
	v_cvt_pk_bf16_f32 v99, v104, v105
	v_cvt_pk_bf16_f32 v100, v100, v101
	v_cvt_pk_bf16_f32 v101, v106, v107
	ds_read_b128 v[102:105], v102
	global_store_dwordx4 v[110:111], v[98:101], off offset:256
	s_waitcnt lgkmcnt(0)
	v_mov_b32_e32 v106, v103
	v_mov_b32_e32 v107, v104
	v_mov_b32_e32 v103, v105
	v_pk_add_f32 v[102:103], v[106:107], v[102:103]
	s_nop 0
	v_add_f32_e32 v102, v102, v103
	v_rcp_f32_e32 v102, v102
	s_nop 0
	v_pk_mul_f32 v[94:95], v[94:95], v[102:103] op_sel_hi:[1,0]
	v_pk_mul_f32 v[98:99], v[92:93], v[102:103] op_sel_hi:[1,0]
	v_pk_mul_f32 v[92:93], v[90:91], v[102:103] op_sel_hi:[1,0]
	v_cvt_pk_bf16_f32 v90, v94, v95
	v_add_co_u32_e32 v94, vcc, s3, v130
	v_pk_mul_f32 v[96:97], v[96:97], v[102:103] op_sel_hi:[1,0]
	s_nop 0
	v_addc_co_u32_e32 v95, vcc, 0, v131, vcc
	v_cvt_pk_bf16_f32 v91, v96, v97
	v_pk_mul_f32 v[86:87], v[86:87], v[102:103] op_sel_hi:[1,0]
	v_cvt_pk_bf16_f32 v92, v92, v93
	v_cvt_pk_bf16_f32 v93, v98, v99
	global_store_dwordx4 v[94:95], v[90:93], off
	v_pk_mul_f32 v[88:89], v[88:89], v[102:103] op_sel_hi:[1,0]
	s_mov_b32 s3, 0x9818000
	v_pk_mul_f32 v[90:91], v[84:85], v[102:103] op_sel_hi:[1,0]
	v_pk_mul_f32 v[84:85], v[82:83], v[102:103] op_sel_hi:[1,0]
	v_cvt_pk_bf16_f32 v82, v86, v87
	v_lshl_add_u32 v86, v142, 4, s2
	v_cvt_pk_bf16_f32 v83, v88, v89
	v_cvt_pk_bf16_f32 v84, v84, v85
	v_cvt_pk_bf16_f32 v85, v90, v91
	ds_read_b128 v[86:89], v86
	global_store_dwordx4 v[94:95], v[82:85], off offset:256
	s_waitcnt lgkmcnt(0)
	v_mov_b32_e32 v90, v87
	v_mov_b32_e32 v91, v88
	v_mov_b32_e32 v87, v89
	v_pk_add_f32 v[86:87], v[90:91], v[86:87]
	s_nop 0
	v_add_f32_e32 v86, v86, v87
	v_rcp_f32_e32 v86, v86
	s_nop 0
	v_pk_mul_f32 v[78:79], v[78:79], v[86:87] op_sel_hi:[1,0]
	v_pk_mul_f32 v[82:83], v[76:77], v[86:87] op_sel_hi:[1,0]
	v_pk_mul_f32 v[76:77], v[74:75], v[86:87] op_sel_hi:[1,0]
	v_cvt_pk_bf16_f32 v74, v78, v79
	v_add_co_u32_e32 v78, vcc, s3, v130
	v_pk_mul_f32 v[80:81], v[80:81], v[86:87] op_sel_hi:[1,0]
	s_nop 0
	v_addc_co_u32_e32 v79, vcc, 0, v131, vcc
	v_cvt_pk_bf16_f32 v75, v80, v81
	v_cvt_pk_bf16_f32 v76, v76, v77
	v_cvt_pk_bf16_f32 v77, v82, v83
	global_store_dwordx4 v[78:79], v[74:77], off
	v_pk_mul_f32 v[72:73], v[72:73], v[86:87] op_sel_hi:[1,0]
	v_pk_mul_f32 v[70:71], v[70:71], v[86:87] op_sel_hi:[1,0]
	v_pk_mul_f32 v[74:75], v[68:69], v[86:87] op_sel_hi:[1,0]
	v_pk_mul_f32 v[68:69], v[66:67], v[86:87] op_sel_hi:[1,0]
	v_cvt_pk_bf16_f32 v66, v70, v71
	v_cvt_pk_bf16_f32 v67, v72, v73
	s_mov_b32 s3, 0x9840000
	v_cvt_pk_bf16_f32 v68, v68, v69
	v_cvt_pk_bf16_f32 v69, v74, v75
	ds_read_b128 v[70:73], v0
	global_store_dwordx4 v[78:79], v[66:69], off offset:256
	s_waitcnt lgkmcnt(0)
	v_mov_b32_e32 v74, v71
	v_mov_b32_e32 v75, v72
	v_mov_b32_e32 v71, v73
	v_pk_add_f32 v[70:71], v[74:75], v[70:71]
	s_nop 0
	v_add_f32_e32 v0, v70, v71
	v_rcp_f32_e32 v0, v0
	s_nop 0
	v_pk_mul_f32 v[62:63], v[62:63], v[0:1] op_sel_hi:[1,0]
	v_pk_mul_f32 v[66:67], v[60:61], v[0:1] op_sel_hi:[1,0]
	v_pk_mul_f32 v[60:61], v[58:59], v[0:1] op_sel_hi:[1,0]
	v_cvt_pk_bf16_f32 v58, v62, v63
	v_add_co_u32_e32 v62, vcc, s3, v130
	v_pk_mul_f32 v[64:65], v[64:65], v[0:1] op_sel_hi:[1,0]
	s_nop 0
	v_addc_co_u32_e32 v63, vcc, 0, v131, vcc
	v_cvt_pk_bf16_f32 v59, v64, v65
	v_cvt_pk_bf16_f32 v60, v60, v61
	v_cvt_pk_bf16_f32 v61, v66, v67
	global_store_dwordx4 v[62:63], v[58:61], off
	v_pk_mul_f32 v[54:55], v[54:55], v[0:1] op_sel_hi:[1,0]
	v_pk_mul_f32 v[10:11], v[10:11], v[0:1] op_sel_hi:[1,0]
	v_pk_mul_f32 v[58:59], v[52:53], v[0:1] op_sel_hi:[1,0]
	v_pk_mul_f32 v[52:53], v[50:51], v[0:1] op_sel_hi:[1,0]
	v_lshl_add_u32 v0, v143, 4, s2
	v_cvt_pk_bf16_f32 v50, v10, v11
	v_cvt_pk_bf16_f32 v51, v54, v55
	v_cvt_pk_bf16_f32 v52, v52, v53
	v_cvt_pk_bf16_f32 v53, v58, v59
	ds_read_b128 v[58:61], v0
	s_mov_b32 s3, 0x9848000
	global_store_dwordx4 v[62:63], v[50:53], off offset:256
	s_waitcnt lgkmcnt(0)
	v_mov_b32_e32 v10, v59
	v_mov_b32_e32 v11, v60
	v_mov_b32_e32 v59, v61
	v_pk_add_f32 v[10:11], v[10:11], v[58:59]
	s_nop 0
	v_add_f32_e32 v0, v10, v11
	v_rcp_f32_e32 v0, v0
	s_nop 0
	v_pk_mul_f32 v[10:11], v[48:49], v[0:1] op_sel_hi:[1,0]
	v_pk_mul_f32 v[46:47], v[46:47], v[0:1] op_sel_hi:[1,0]
	v_pk_mul_f32 v[42:43], v[42:43], v[0:1] op_sel_hi:[1,0]
	v_cvt_pk_bf16_f32 v46, v46, v47
	v_cvt_pk_bf16_f32 v47, v10, v11
	v_add_co_u32_e32 v10, vcc, s3, v130
	v_pk_mul_f32 v[50:51], v[56:57], v[0:1] op_sel_hi:[1,0]
	v_cvt_pk_bf16_f32 v48, v42, v43
	s_nop 0
	v_addc_co_u32_e32 v11, vcc, 0, v131, vcc
	v_cvt_pk_bf16_f32 v49, v50, v51
	v_pk_mul_f32 v[38:39], v[38:39], v[0:1] op_sel_hi:[1,0]
	v_pk_mul_f32 v[6:7], v[6:7], v[0:1] op_sel_hi:[1,0]
	v_pk_mul_f32 v[42:43], v[36:37], v[0:1] op_sel_hi:[1,0]
	v_pk_mul_f32 v[36:37], v[34:35], v[0:1] op_sel_hi:[1,0]
	v_lshl_add_u32 v0, v144, 4, s2
	global_store_dwordx4 v[10:11], v[46:49], off
	v_cvt_pk_bf16_f32 v34, v6, v7
	v_cvt_pk_bf16_f32 v35, v38, v39
	v_cvt_pk_bf16_f32 v36, v36, v37
	v_cvt_pk_bf16_f32 v37, v42, v43
	ds_read_b128 v[46:49], v0
	global_store_dwordx4 v[10:11], v[34:37], off offset:256
	s_mov_b32 s3, 0x9850000
	s_waitcnt lgkmcnt(0)
	v_mov_b32_e32 v6, v47
	v_mov_b32_e32 v7, v48
	v_mov_b32_e32 v47, v49
	v_pk_add_f32 v[6:7], v[6:7], v[46:47]
	s_nop 0
	v_add_f32_e32 v0, v6, v7
	v_rcp_f32_e32 v0, v0
	s_nop 0
	v_pk_mul_f32 v[10:11], v[30:31], v[0:1] op_sel_hi:[1,0]
	v_pk_mul_f32 v[6:7], v[32:33], v[0:1] op_sel_hi:[1,0]
	v_pk_mul_f32 v[30:31], v[28:29], v[0:1] op_sel_hi:[1,0]
	v_cvt_pk_bf16_f32 v28, v10, v11
	v_add_co_u32_e32 v10, vcc, s3, v130
	v_pk_mul_f32 v[32:33], v[44:45], v[0:1] op_sel_hi:[1,0]
	v_cvt_pk_bf16_f32 v29, v6, v7
	s_nop 0
	v_addc_co_u32_e32 v11, vcc, 0, v131, vcc
	v_pk_mul_f32 v[6:7], v[22:23], v[0:1] op_sel_hi:[1,0]
	v_pk_mul_f32 v[4:5], v[4:5], v[0:1] op_sel_hi:[1,0]
	v_pk_mul_f32 v[22:23], v[26:27], v[0:1] op_sel_hi:[1,0]
	v_pk_mul_f32 v[18:19], v[18:19], v[0:1] op_sel_hi:[1,0]
	v_lshl_add_u32 v0, v145, 4, s2
	v_cvt_pk_bf16_f32 v30, v30, v31
	v_cvt_pk_bf16_f32 v31, v32, v33
	global_store_dwordx4 v[10:11], v[28:31], off
	v_cvt_pk_bf16_f32 v4, v4, v5
	v_cvt_pk_bf16_f32 v5, v6, v7
	v_cvt_pk_bf16_f32 v6, v18, v19
	v_cvt_pk_bf16_f32 v7, v22, v23
	ds_read_b128 v[26:29], v0
	global_store_dwordx4 v[10:11], v[4:7], off offset:256
	s_mov_b32 s2, 0x9858000
	s_waitcnt lgkmcnt(0)
	v_mov_b32_e32 v18, v27
	v_mov_b32_e32 v19, v28
	v_mov_b32_e32 v27, v29
	v_pk_add_f32 v[18:19], v[18:19], v[26:27]
	s_nop 0
	v_add_f32_e32 v0, v18, v19
	v_rcp_f32_e32 v0, v0
	s_nop 0
	v_pk_mul_f32 v[6:7], v[20:21], v[0:1] op_sel_hi:[1,0]
	v_pk_mul_f32 v[4:5], v[14:15], v[0:1] op_sel_hi:[1,0]
	v_pk_mul_f32 v[10:11], v[40:41], v[0:1] op_sel_hi:[1,0]
	v_pk_mul_f32 v[14:15], v[24:25], v[0:1] op_sel_hi:[1,0]
	v_cvt_pk_bf16_f32 v4, v4, v5
	v_cvt_pk_bf16_f32 v5, v6, v7
	v_pk_mul_f32 v[2:3], v[2:3], v[0:1] op_sel_hi:[1,0]
	v_cvt_pk_bf16_f32 v6, v14, v15
	v_cvt_pk_bf16_f32 v7, v10, v11
	v_add_co_u32_e32 v10, vcc, s2, v130
	s_nop 1
	v_addc_co_u32_e32 v11, vcc, 0, v131, vcc
	global_store_dwordx4 v[10:11], v[4:7], off
	v_cvt_pk_bf16_f32 v2, v2, v3
	s_nop 1
	v_pk_mul_f32 v[4:5], v[8:9], v[0:1] op_sel_hi:[1,0]
	v_pk_mul_f32 v[6:7], v[16:17], v[0:1] op_sel_hi:[1,0]
	v_pk_mul_f32 v[8:9], v[12:13], v[0:1] op_sel_hi:[1,0]
	v_cvt_pk_bf16_f32 v3, v4, v5
	s_nop 0
	v_cvt_pk_bf16_f32 v4, v8, v9
	v_cvt_pk_bf16_f32 v5, v6, v7
	global_store_dwordx4 v[10:11], v[2:5], off offset:256
